# attention softmax: 16-value row max rewritten as two interleaved v_max3 chains (8 ops instead of hipcc's 12 canonicalising v_max + 6 v_max3), canonicalising v_max before the cross-lane max steps dropp
# speedup vs baseline: 1.0064x; 1.0039x over previous
; __device__ __forceinline__ void attn_unit(const WS& ws, int u, bool dry = false) {
;     ...
;     for (int nt = 0; nt < 2; ++nt) {
;       float mx = -INFINITY;
; #pragma unroll
;       for (int mt = 0; mt < 4; ++mt) mx = fmaxf(mx, fmaxf(fmaxf(s[mt][nt][0], s[mt][nt][1]), fmaxf(s[mt][nt][2], s[mt][nt][3])));
;       mx = fmaxf(mx, __shfl_xor(mx, 16)); mx = fmaxf(mx, __shfl_xor(mx, 32));
;       if (__builtin_amdgcn_ballot_w64(mx > mrun[nt]) != 0ull) {
;         const float mnew = fmaxf(mrun[nt], mx);
;         const float alpha = __builtin_amdgcn_exp2f(mrun[nt] - mnew);
;         mrun[nt] = mnew;
;         lsum[nt] *= alpha;
; #pragma unroll
;         for (int mt = 0; mt < 4; ++mt) oacc[mt][nt] = scale4(oacc[mt][nt], alpha);
;       }
.LBB0_865:
	s_nop 1
	v_max3_f32 v130, v114, v115, v116
	v_max3_f32 v131, v117, v118, v119
	v_max3_f32 v130, v130, v120, v121
	v_max3_f32 v131, v131, v122, v123
	v_max3_f32 v130, v130, v124, v125
	v_max3_f32 v131, v131, v126, v127
	v_max3_f32 v130, v130, v128, v129
	v_max_f32_e32 v130, v130, v131
	ds_bpermute_b32 v131, v170, v130
	s_waitcnt lgkmcnt(0)
	v_max_f32_e32 v130, v130, v131
	ds_bpermute_b32 v131, v168, v130
	s_waitcnt lgkmcnt(0)
	v_max_f32_e32 v130, v130, v131
	v_cmp_gt_f32_e32 vcc, v130, v203
	s_cbranch_vccz .LBB0_867
	v_max_f32_e32 v130, v130, v130
	v_max_f32_e32 v131, v203, v203
	v_max_f32_e32 v130, v131, v130
	v_sub_f32_e32 v131, v203, v130
	v_exp_f32_e32 v131, v131
	v_mov_b32_e32 v203, v130
	v_mov_b32_e32 v132, v131
	v_mul_f32_e32 v201, v201, v131
	v_mul_f32_e32 v94, v94, v132
	v_mul_f32_e32 v95, v95, v132
	v_mul_f32_e32 v96, v96, v132
	v_mul_f32_e32 v97, v97, v132
	v_mov_b32_e32 v132, v131
	s_nop 0
	v_mul_f32_e32 v90, v90, v132
	v_mul_f32_e32 v91, v91, v132
	v_mul_f32_e32 v92, v92, v132
	v_mul_f32_e32 v93, v93, v132
	v_mov_b32_e32 v132, v131
	s_nop 0
	v_mul_f32_e32 v74, v74, v132
	v_mul_f32_e32 v75, v75, v132
	v_mul_f32_e32 v76, v76, v132
	v_mul_f32_e32 v77, v77, v132
	s_nop 0
	v_mul_f32_e32 v66, v66, v131
	v_mul_f32_e32 v67, v67, v131
	v_mul_f32_e32 v68, v68, v131
	v_mul_f32_e32 v69, v69, v131
.LBB0_867:
	v_max3_f32 v130, v98, v99, v100
	v_max3_f32 v131, v101, v102, v103
	v_max3_f32 v130, v130, v104, v105
	v_max3_f32 v131, v131, v106, v107
	v_max3_f32 v130, v130, v108, v109
	v_max3_f32 v131, v131, v110, v111
	v_max3_f32 v130, v130, v112, v113
	v_max_f32_e32 v130, v130, v131
	ds_bpermute_b32 v131, v170, v130
	s_waitcnt lgkmcnt(0)
	v_max_f32_e32 v130, v130, v131
	ds_bpermute_b32 v131, v168, v130
	s_waitcnt lgkmcnt(0)
	v_max_f32_e32 v130, v130, v131
	v_cmp_gt_f32_e32 vcc, v130, v202
	s_cbranch_vccz .LBB0_869
	v_max_f32_e32 v130, v130, v130
	v_max_f32_e32 v131, v202, v202
	v_max_f32_e32 v130, v131, v130
	v_sub_f32_e32 v131, v202, v130
	v_exp_f32_e32 v131, v131
	v_mov_b32_e32 v202, v130
	v_mov_b32_e32 v132, v131
	v_mul_f32_e32 v176, v176, v131
	v_mul_f32_e32 v62, v62, v132
	v_mul_f32_e32 v63, v63, v132
	v_mul_f32_e32 v64, v64, v132
	v_mul_f32_e32 v65, v65, v132
	v_mov_b32_e32 v132, v131
	s_nop 0
	v_mul_f32_e32 v46, v46, v132
	v_mul_f32_e32 v47, v47, v132
	v_mul_f32_e32 v48, v48, v132
	v_mul_f32_e32 v49, v49, v132
	v_mov_b32_e32 v132, v131
	s_nop 0
	v_mul_f32_e32 v38, v38, v132
	v_mul_f32_e32 v39, v39, v132
	v_mul_f32_e32 v40, v40, v132
	v_mul_f32_e32 v41, v41, v132
	s_nop 0
	v_mul_f32_e32 v34, v34, v131
	v_mul_f32_e32 v35, v35, v131
	v_mul_f32_e32 v36, v36, v131
	v_mul_f32_e32 v37, v37, v131

; __device__ __forceinline__ void attn_unit(const WS& ws, int u, bool dry = false) {
;     ...
;     for (int nt = 0; nt < 2; ++nt) {
;       float mx = -INFINITY;
; #pragma unroll
;       for (int mt = 0; mt < 4; ++mt) mx = fmaxf(mx, fmaxf(fmaxf(s[mt][nt][0], s[mt][nt][1]), fmaxf(s[mt][nt][2], s[mt][nt][3])));
;       mx = fmaxf(mx, __shfl_xor(mx, 16)); mx = fmaxf(mx, __shfl_xor(mx, 32));
;       if (__builtin_amdgcn_ballot_w64(mx > mrun[nt]) != 0ull) {
;         const float mnew = fmaxf(mrun[nt], mx);
;         const float alpha = __builtin_amdgcn_exp2f(mrun[nt] - mnew);
;         mrun[nt] = mnew;
;         lsum[nt] *= alpha;
; #pragma unroll
;         for (int mt = 0; mt < 4; ++mt) oacc[mt][nt] = scale4(oacc[mt][nt], alpha);
;       }
;       const float mnew = mrun[nt];
;       float ps = 0.f;
; #pragma unroll
;       for (int mt = 0; mt < 4; ++mt)
; #pragma unroll
;         for (int jj = 0; jj < 4; ++jj) { const float pv = __builtin_amdgcn_exp2f(s[mt][nt][jj] - mnew); s[mt][nt][jj] = pv; ps += pv; }
;       lsum[nt] += ps;
.LBB0_871:
	v_add_f32_e32 v66, 0, v227
	v_add_f32_e32 v66, v228, v66
	v_add_f32_e32 v66, v229, v66
	v_add_f32_e32 v66, v230, v66
	v_max3_f32 v67, v114, v115, v116
	v_max3_f32 v68, v117, v118, v119
	v_max3_f32 v67, v67, v120, v121
	v_max3_f32 v68, v68, v122, v123
	v_max3_f32 v67, v67, v124, v125
	v_max3_f32 v68, v68, v126, v127
	v_max3_f32 v67, v67, v128, v129
	v_max_f32_e32 v67, v67, v68
	v_add_f32_e32 v66, v231, v66
	ds_bpermute_b32 v68, v170, v67
	v_add_f32_e32 v66, v232, v66
	v_add_f32_e32 v66, v233, v66
	v_add_f32_e32 v66, v234, v66
	v_add_f32_e32 v66, v235, v66
	v_add_f32_e32 v66, v204, v66
	s_waitcnt lgkmcnt(0)
	v_add_f32_e32 v66, v221, v66
	v_max_f32_e32 v67, v67, v68
	v_add_f32_e32 v66, v223, v66
	ds_bpermute_b32 v68, v168, v67
	v_add_f32_e32 v66, v225, v66
	v_add_f32_e32 v66, v222, v66
	v_add_f32_e32 v66, v224, v66
	v_add_f32_e32 v66, v226, v66
	v_add_f32_e32 v221, v201, v66
	s_waitcnt lgkmcnt(0)
	v_max_f32_e32 v66, v67, v68
	v_cmp_gt_f32_e32 vcc, v66, v203
	s_cbranch_vccz .LBB0_879
	v_max_f32_e32 v66, v66, v66
	v_max_f32_e32 v67, v203, v203
	v_max_f32_e32 v204, v67, v66
	v_sub_f32_e32 v66, v203, v204
	v_exp_f32_e32 v69, v66
	s_nop 0
	v_mov_b32_e32 v66, v69
	v_mul_f32_e32 v201, v221, v69
	v_mul_f32_e32 v110, v130, v66
	v_mul_f32_e32 v111, v131, v66
	v_mul_f32_e32 v112, v132, v66
	v_mul_f32_e32 v113, v133, v66
	v_mov_b32_e32 v66, v69
	s_nop 0
	v_mul_f32_e32 v102, v134, v66
	v_mul_f32_e32 v103, v135, v66
	v_mul_f32_e32 v104, v136, v66
	v_mul_f32_e32 v105, v137, v66
	v_mov_b32_e32 v66, v69
	s_nop 0
	v_mul_f32_e32 v74, v138, v66
	v_mul_f32_e32 v75, v139, v66
	v_mul_f32_e32 v76, v140, v66
	v_mul_f32_e32 v77, v141, v66
	s_nop 0
	v_mul_f32_e32 v66, v142, v69
	v_mul_f32_e32 v67, v143, v69
	v_mul_f32_e32 v68, v144, v69
	v_mul_f32_e32 v69, v145, v69
	s_cbranch_execnz .LBB0_874

; __device__ __forceinline__ void attn_unit(const WS& ws, int u, bool dry = false) {
;     ...
;     for (int nt = 0; nt < 2; ++nt) {
;       float mx = -INFINITY;
; #pragma unroll
;       for (int mt = 0; mt < 4; ++mt) mx = fmaxf(mx, fmaxf(fmaxf(s[mt][nt][0], s[mt][nt][1]), fmaxf(s[mt][nt][2], s[mt][nt][3])));
;       mx = fmaxf(mx, __shfl_xor(mx, 16)); mx = fmaxf(mx, __shfl_xor(mx, 32));
;       if (__builtin_amdgcn_ballot_w64(mx > mrun[nt]) != 0ull) {
;         const float mnew = fmaxf(mrun[nt], mx);
;         const float alpha = __builtin_amdgcn_exp2f(mrun[nt] - mnew);
;         mrun[nt] = mnew;
;         lsum[nt] *= alpha;
; #pragma unroll
;         for (int mt = 0; mt < 4; ++mt) oacc[mt][nt] = scale4(oacc[mt][nt], alpha);
;       }
;       const float mnew = mrun[nt];
;       float ps = 0.f;
; #pragma unroll
;       for (int mt = 0; mt < 4; ++mt)
; #pragma unroll
;         for (int jj = 0; jj < 4; ++jj) { const float pv = __builtin_amdgcn_exp2f(s[mt][nt][jj] - mnew); s[mt][nt][jj] = pv; ps += pv; }
;       lsum[nt] += ps;
.LBB0_874:
	v_add_f32_e32 v130, 0, v208
	v_add_f32_e32 v130, v209, v130
	v_add_f32_e32 v130, v210, v130
	v_add_f32_e32 v130, v211, v130
	v_max3_f32 v131, v34, v35, v36
	v_max3_f32 v132, v37, v38, v39
	v_max3_f32 v131, v131, v40, v41
	v_max3_f32 v132, v132, v46, v47
	v_max3_f32 v131, v131, v48, v49
	v_max3_f32 v132, v132, v62, v63
	v_max3_f32 v131, v131, v64, v65
	v_max_f32_e32 v131, v131, v132
	v_add_f32_e32 v130, v212, v130
	ds_bpermute_b32 v132, v170, v131
	v_add_f32_e32 v130, v213, v130
	v_add_f32_e32 v130, v214, v130
	v_add_f32_e32 v130, v215, v130
	v_add_f32_e32 v130, v216, v130
	v_add_f32_e32 v130, v205, v130
	s_waitcnt lgkmcnt(0)
	v_add_f32_e32 v130, v206, v130
	v_max_f32_e32 v131, v131, v132
	v_add_f32_e32 v130, v207, v130
	ds_bpermute_b32 v132, v168, v131
	v_add_f32_e32 v130, v219, v130
	v_add_f32_e32 v130, v217, v130
	v_add_f32_e32 v130, v218, v130
	v_add_f32_e32 v130, v220, v130
	v_add_f32_e32 v205, v176, v130
	s_waitcnt lgkmcnt(0)
	v_max_f32_e32 v130, v131, v132
	v_cmp_gt_f32_e32 vcc, v130, v202
	s_cbranch_vccz .LBB0_880
	v_max_f32_e32 v130, v130, v130
	v_max_f32_e32 v131, v202, v202
	v_max_f32_e32 v203, v131, v130
	v_sub_f32_e32 v130, v202, v203
	v_exp_f32_e32 v133, v130
	s_nop 0
	v_mov_b32_e32 v130, v133
	v_mul_f32_e32 v176, v205, v133
	v_mul_f32_e32 v142, v94, v130
	v_mul_f32_e32 v143, v95, v130
	v_mul_f32_e32 v144, v96, v130
	v_mul_f32_e32 v145, v97, v130
	v_mov_b32_e32 v130, v133
	s_nop 0
	v_mul_f32_e32 v138, v90, v130
	v_mul_f32_e32 v139, v91, v130
	v_mul_f32_e32 v140, v92, v130
	v_mul_f32_e32 v141, v93, v130
	v_mov_b32_e32 v130, v133
	s_nop 0
	v_mul_f32_e32 v134, v98, v130
	v_mul_f32_e32 v135, v99, v130
	v_mul_f32_e32 v136, v100, v130
	v_mul_f32_e32 v137, v101, v130
	s_nop 0
	v_mul_f32_e32 v130, v106, v133
	v_mul_f32_e32 v131, v107, v133
	v_mul_f32_e32 v132, v108, v133
	v_mul_f32_e32 v133, v109, v133
	s_cbranch_execnz .LBB0_877
